# final RMSNorm of the first half streamed from inside FFN1(half 1) tile epilogues (overlaps HBM traffic with MFMA phases)
# speedup vs baseline: 1.0034x; 1.0031x over previous
.LBB0_679:
.LBB0_680:
	s_cmp_gt_i32 s94, s0
	s_cselect_b64 s[0:1], -1, 0
	s_xor_b64 s[16:17], s[16:17], -1
	s_or_b64 s[0:1], s[0:1], s[16:17]
	s_and_b64 vcc, exec, s[0:1]
	s_cbranch_vccnz .LBB0_697
	s_mov_b32 s99, 0
	s_load_dword s0, s[42:43], 0x0
	s_waitcnt vmcnt(10)
	v_mov_b32_e32 v13, v150
	s_waitcnt lgkmcnt(0)
	v_mov_b32_e32 v0, s0
	s_nop 0
	v_readfirstlane_b32 s52, v0
	v_mov_b32_e32 v0, v151
	s_nop 0
	v_readfirstlane_b32 s0, v0
	v_readfirstlane_b32 s17, v13
	s_cmpk_gt_i32 s0, 0x15ff
	s_cbranch_scc1 .LBB0_697
	v_lshlrev_b32_e32 v0, 4, v13
	v_add_u32_e32 v1, 0x2000, v0
	v_ashrrev_i32_e32 v2, 31, v1
	v_lshrrev_b32_e32 v2, 22, v2
	v_add_u32_e32 v2, v1, v2
	v_ashrrev_i32_e32 v8, 10, v2
	v_mul_i32_i24_e32 v2, 0x400, v8
	v_sub_u32_e32 v1, v1, v2
	v_lshrrev_b32_e32 v2, 4, v1
	v_bitop3_b32 v1, v2, v1, 32 bitop3:0x6c
	v_ashrrev_i32_e32 v2, 31, v1
	v_lshrrev_b32_e32 v2, 26, v2
	v_add_u32_e32 v2, v1, v2
	v_lshlrev_b32_e32 v3, 3, v8
	v_ashrrev_i32_e32 v9, 6, v2
	v_and_b32_e32 v3, -16, v3
	v_add_u32_e32 v3, v9, v3
	v_and_b32_e32 v4, 3, v9
	s_mov_b32 s16, 0xfffe0
	v_lshrrev_b32_e32 v5, 2, v3
	v_lshlrev_b32_e32 v6, 1, v3
	v_and_b32_e32 v2, 0xc0, v2
	v_and_or_b32 v4, v3, s16, v4
	v_and_b32_e32 v5, 4, v5
	v_and_b32_e32 v6, 24, v6
	v_sub_u32_e32 v1, v1, v2
	v_or3_b32 v4, v4, v5, v6
	v_lshlrev_b32_e32 v5, 5, v8
	v_ashrrev_i16_sdwa v1, v152, sext(v1) dst_sel:DWORD dst_unused:UNUSED_PAD src0_sel:DWORD src1_sel:BYTE_0
	v_and_b32_e32 v5, 32, v5
	v_bfe_i32 v10, v1, 0, 16
	v_add_lshl_u32 v1, v5, v10, 1
	v_lshl_add_u32 v138, v4, 12, v1
	v_lshl_add_u32 v140, v3, 12, v1
	v_bfe_i32 v1, v13, 27, 1
	v_lshrrev_b32_e32 v1, 22, v1
	v_add_u32_e32 v1, v0, v1
	v_and_b32_e32 v1, 0xfffffc00, v1
	v_sub_u32_e32 v0, v0, v1
	v_lshrrev_b32_e32 v1, 4, v0
	v_bitop3_b32 v1, v1, v0, 32 bitop3:0x6c
	v_ashrrev_i32_e32 v0, 31, v0
	v_lshrrev_b32_e32 v0, 26, v0
	v_add_u32_e32 v0, v1, v0
	v_ashrrev_i32_e32 v11, 6, v0
	v_ashrrev_i32_e32 v0, 31, v13
	v_lshrrev_b32_e32 v0, 26, v0
	v_add_u32_e32 v0, v13, v0
	v_ashrrev_i32_e32 v12, 6, v0
	s_lshl_b32 s1, s59, 27
	v_lshlrev_b32_e32 v0, 3, v12
	s_add_u32 s1, s2, s1
	v_and_b32_e32 v0, -16, v0
	s_addc_u32 s58, s3, 0
	v_add_u32_e32 v0, v11, v0
	v_and_b32_e32 v2, 3, v11
	s_ashr_i32 s37, s0, 31
	v_and_or_b32 v2, v0, s16, v2
	s_lshr_b32 s16, s37, 29
	s_add_i32 s16, s0, s16
	s_ashr_i32 s22, s17, 6
	s_ashr_i32 s18, s16, 3
	s_and_b32 s16, s16, -8
	s_ashr_i32 s23, s17, 8
	s_lshl_b32 s36, s22, 10
	s_sub_i32 s16, s0, s16
	s_cmp_lt_i32 s16, 0
	s_movk_i32 s19, 0x2c1
	s_cselect_b32 s19, s19, 0x2c0
	s_mul_i32 s16, s16, s19
	s_add_i32 s16, s16, s18
	s_mul_hi_i32 s18, s16, 0x2e8ba2e9
	s_lshr_b32 s19, s18, 31
	s_ashr_i32 s18, s18, 6
	s_add_i32 s18, s18, s19
	s_lshl_b32 s19, s18, 3
	s_mulk_i32 s18, 0x160
	s_sub_i32 s18, s16, s18
	s_bfe_u32 s16, s18, 0x3001c
	s_add_i32 s20, s18, s16
	s_sext_i32_i16 s16, s20
	s_and_b32 s20, s20, 0xfff8
	v_lshrrev_b32_e32 v3, 2, v0
	v_lshlrev_b32_e32 v4, 1, v0
	s_sub_i32 s18, s18, s20
	v_and_b32_e32 v3, 4, v3
	v_and_b32_e32 v4, 24, v4
	s_sext_i32_i16 s18, s18
	v_or3_b32 v2, v2, v3, v4
	v_mul_i32_i24_e32 v4, 64, v11
	s_lshr_b32 s16, s16, 3
	s_add_i32 s18, s19, s18
	v_sub_u32_e32 v1, v1, v4
	s_ashr_i32 s19, s18, 31
	s_bfe_i64 s[24:25], s[16:17], 0x100000
	v_lshlrev_b32_e32 v3, 5, v12
	v_ashrrev_i16_sdwa v1, v152, sext(v1) dst_sel:DWORD dst_unused:UNUSED_PAD src0_sel:DWORD src1_sel:BYTE_0
	s_lshl_b64 s[20:21], s[18:19], 20
	s_lshl_b64 s[24:25], s[24:25], 20
	v_and_b32_e32 v3, 32, v3
	s_waitcnt vmcnt(9)
	v_bfe_i32 v14, v1, 0, 16
	s_add_u32 s26, s33, s24
	v_add_lshl_u32 v1, v3, v14, 1
	s_addc_u32 s27, s30, s25
	s_add_i32 s50, s36, 0
	v_lshl_add_u32 v128, v2, 12, v1
	s_add_i32 m0, s50, 0x10000
	v_lshl_add_u32 v142, v0, 12, v1
	global_load_lds_dwordx4 v128, s[26:27]
	s_add_i32 m0, s50, 0x12000
	s_add_u32 s24, s26, 0x80000
	global_load_lds_dwordx4 v138, s[26:27]
	s_addc_u32 s25, s27, 0
	s_add_i32 m0, s50, 0x14000
	v_mov_b32_e32 v139, v129
	global_load_lds_dwordx4 v128, s[24:25]
	s_add_i32 m0, s50, 0x16000
	s_add_u32 s20, s1, s20
	s_addc_u32 s21, s58, s21
	s_add_i32 s51, s50, 0x2000
	global_load_lds_dwordx4 v138, s[24:25]
	s_mov_b32 m0, s50
	s_add_u32 s24, s20, 0x80000
	global_load_lds_dwordx4 v142, s[20:21]
	s_mov_b32 m0, s51
	s_addc_u32 s25, s21, 0
	s_add_i32 s86, s50, 0x4000
	global_load_lds_dwordx4 v140, s[20:21]
	s_mov_b32 m0, s86
	s_add_i32 s87, s50, 0x6000
	global_load_lds_dwordx4 v142, s[24:25]
	s_mov_b32 m0, s87
	v_mov_b32_e32 v143, v129
	global_load_lds_dwordx4 v140, s[24:25]
	v_mov_b32_e32 v141, v129
	s_cmp_eq_u32 s23, 1
	v_lshl_add_u64 v[6:7], s[26:27], 0, v[128:129]
	v_lshl_add_u64 v[4:5], s[26:27], 0, v[138:139]
	v_lshl_add_u64 v[0:1], s[20:21], 0, v[142:143]
	s_cselect_b64 s[40:41], -1, 0
	s_cmp_lg_u32 s23, 1
	v_lshl_add_u64 v[2:3], s[20:21], 0, v[140:141]
	s_cbranch_scc1 .LBB0_684
	s_barrier

.LBB0_693:
	s_cmp_eq_u32 s59, 1
	s_cbranch_scc0 .Lfn_skip_ld
	s_cmp_lt_u32 s99, 16
	s_cbranch_scc0 .Lfn_skip_ld
	v_readfirstlane_b32 s100, v151
	v_readfirstlane_b32 s101, v150
	v_and_b32_e32 v213, 63, v150
	s_lshl_b32 s100, s100, 3
	s_lshr_b32 s101, s101, 6
	s_add_u32 s100, s100, s101
	s_lshl_b32 s101, s99, 11
	s_add_u32 s100, s100, s101
	s_lshl_b32 s101, s100, 12
	s_add_u32 s101, s101, 0x6400000
	v_lshlrev_b32_e32 v214, 4, v213
	v_add_u32_e32 v214, s101, v214
	v_mov_b32_e32 v215, 0
	v_lshl_add_u64 v[214:215], s[92:93], 0, v[214:215]
	s_lshl_b32 s101, s100, 2
	s_add_u32 s101, s101, 0x5f80000
	v_mov_b32_e32 v216, s101
	v_mov_b32_e32 v217, 0
	v_lshl_add_u64 v[216:217], s[92:93], 0, v[216:217]
	s_lshl_b32 s101, s100, 13
	s_add_u32 s101, s101, 0x1000
	v_lshlrev_b32_e32 v218, 5, v213
	v_add_u32_e32 v218, s101, v218
	v_mov_b32_e32 v219, 0
	v_lshl_add_u64 v[218:219], s[90:91], 0, v[218:219]
	v_lshlrev_b32_e32 v228, 5, v213
	v_mov_b32_e32 v229, 0
	v_lshl_add_u64 v[228:229], s[88:89], 0, v[228:229]
	s_mov_b64 s[100:101], 0x1000
	v_lshl_add_u64 v[230:231], v[228:229], 0, s[100:101]
	global_load_dword v212, v[216:217], off
	global_load_dwordx4 v[164:167], v[214:215], off
	global_load_dwordx4 v[168:171], v[214:215], off offset:1024
	global_load_dwordx4 v[172:175], v[214:215], off offset:2048
	global_load_dwordx4 v[176:179], v[214:215], off offset:3072
	global_load_dwordx4 v[180:183], v[228:229], off
	global_load_dwordx4 v[184:187], v[228:229], off offset:16
	global_load_dwordx4 v[188:191], v[228:229], off offset:2048
	global_load_dwordx4 v[192:195], v[228:229], off offset:2064
	global_load_dwordx4 v[196:199], v[230:231], off
	global_load_dwordx4 v[200:203], v[230:231], off offset:16
	global_load_dwordx4 v[204:207], v[230:231], off offset:2048
	global_load_dwordx4 v[208:211], v[230:231], off offset:2064
.Lfn_skip_ld:
	v_lshl_add_u32 v159, s18, 8, v155
	v_add_u32_e32 v160, s44, v159
	v_ashrrev_i32_e32 v161, 31, v160
	v_lshl_add_u64 v[160:161], v[160:161], 2, s[6:7]
	global_load_dword v160, v[160:161], off
	v_mov_b32_e32 v162, v120
	v_mov_b32_e32 v163, v124
	v_mov_b32_e32 v124, v121
	v_lshl_or_b32 v148, s19, 7, v157
	v_ashrrev_i32_e32 v149, 31, v148
	s_waitcnt vmcnt(0)
	v_fmamk_f32 v160, v160, 0x3a000000, v153
	v_cmp_gt_f32_e32 vcc, s14, v160
	v_mul_f32_e32 v161, 0x4b800000, v160
	s_nop 0
	v_cndmask_b32_e32 v160, v160, v161, vcc
	v_rsq_f32_e32 v160, v160
	s_nop 0
	v_mul_f32_e32 v161, 0x45800000, v160
	v_cndmask_b32_e32 v160, v160, v161, vcc
	v_pk_mul_f32 v[162:163], v[162:163], v[160:161] op_sel_hi:[1,0]
	s_nop 0
	v_mul_f32_e32 v120, 0xbfb8aa3b, v163
	v_exp_f32_e32 v120, v120
	s_nop 0
	v_add_f32_e32 v120, 1.0, v120
	v_rcp_f32_e32 v120, v120
	s_nop 0
	v_mul_f32_e32 v120, v163, v120
	v_mul_f32_e32 v161, v162, v120
	v_pk_mul_f32 v[120:121], v[124:125], v[160:161] op_sel_hi:[1,0]
	s_nop 0
	v_mul_f32_e32 v124, 0xbfb8aa3b, v121
	v_exp_f32_e32 v124, v124
	s_nop 0
	v_add_f32_e32 v124, 1.0, v124
	v_rcp_f32_e32 v124, v124
	s_nop 0
	v_mul_f32_e32 v121, v121, v124
	v_mul_f32_e32 v124, v120, v121
	v_mov_b32_e32 v120, v122
	v_mov_b32_e32 v121, v126
	v_pk_mul_f32 v[120:121], v[120:121], v[160:161] op_sel_hi:[1,0]
	v_mov_b32_e32 v126, v123
	v_mul_f32_e32 v122, 0xbfb8aa3b, v121
	v_exp_f32_e32 v122, v122
	s_nop 0
	v_add_f32_e32 v122, 1.0, v122
	v_rcp_f32_e32 v122, v122
	s_nop 0
	v_mul_f32_e32 v121, v121, v122
	v_mul_f32_e32 v122, v120, v121
	v_pk_mul_f32 v[120:121], v[126:127], v[160:161] op_sel_hi:[1,0]
	s_nop 0
	v_mul_f32_e32 v123, 0xbfb8aa3b, v121
	v_exp_f32_e32 v123, v123
	s_nop 0
	v_add_f32_e32 v123, 1.0, v123
	v_rcp_f32_e32 v123, v123
	s_nop 0
	v_mul_f32_e32 v121, v121, v123
	v_mul_f32_e32 v123, v120, v121
	v_mov_b32_e32 v120, v112
	v_mov_b32_e32 v121, v116
	v_pk_mul_f32 v[120:121], v[120:121], v[160:161] op_sel_hi:[1,0]
	v_mov_b32_e32 v116, v113
	v_mul_f32_e32 v112, 0xbfb8aa3b, v121
	v_exp_f32_e32 v112, v112
	s_nop 0
	v_add_f32_e32 v112, 1.0, v112
	v_rcp_f32_e32 v112, v112
	s_nop 0
	v_mul_f32_e32 v112, v121, v112
	v_mul_f32_e32 v120, v120, v112
	v_pk_mul_f32 v[112:113], v[116:117], v[160:161] op_sel_hi:[1,0]
	s_nop 0
	v_mul_f32_e32 v116, 0xbfb8aa3b, v113
	v_exp_f32_e32 v116, v116
	s_nop 0
	v_add_f32_e32 v116, 1.0, v116
	v_rcp_f32_e32 v116, v116
	s_nop 0
	v_mul_f32_e32 v113, v113, v116
	v_mul_f32_e32 v121, v112, v113
	v_mov_b32_e32 v112, v114
	v_mov_b32_e32 v113, v118
	v_pk_mul_f32 v[112:113], v[112:113], v[160:161] op_sel_hi:[1,0]
	v_mov_b32_e32 v118, v115
	v_mul_f32_e32 v114, 0xbfb8aa3b, v113
	v_exp_f32_e32 v114, v114
	v_cvt_pk_bf16_f32 v116, v161, v124
	v_cvt_pk_bf16_f32 v117, v122, v123
	s_nop 0
	v_add_f32_e32 v114, 1.0, v114
	v_rcp_f32_e32 v114, v114
	s_nop 0
	v_mul_f32_e32 v113, v113, v114
	v_mul_f32_e32 v114, v112, v113
	v_pk_mul_f32 v[112:113], v[118:119], v[160:161] op_sel_hi:[1,0]
	v_cvt_pk_bf16_f32 v118, v120, v121
	s_nop 0
	v_mul_f32_e32 v115, 0xbfb8aa3b, v113
	v_exp_f32_e32 v115, v115
	s_nop 0
	v_add_f32_e32 v115, 1.0, v115
	v_rcp_f32_e32 v115, v115
	s_nop 0
	v_mul_f32_e32 v113, v113, v115
	v_mul_f32_e32 v112, v112, v113
	v_cvt_pk_bf16_f32 v119, v114, v112
	v_mov_b64_e32 v[112:113], s[4:5]
	v_mad_i64_i32 v[120:121], s[18:19], v159, s15, v[112:113]
	v_lshlrev_b64 v[114:115], 1, v[148:149]
	v_lshl_add_u64 v[120:121], v[120:121], 0, v[114:115]
	global_store_dwordx4 v[120:121], v[116:119], off
	v_or_b32_e32 v120, 16, v159
	s_nop 0
	v_add_u32_e32 v116, s44, v120
	v_ashrrev_i32_e32 v117, 31, v116
	v_lshl_add_u64 v[116:117], v[116:117], 2, s[6:7]
	global_load_dword v116, v[116:117], off
	v_mov_b32_e32 v118, v104
	v_mov_b32_e32 v119, v108
	v_mov_b32_e32 v108, v105
	s_waitcnt vmcnt(0)
	v_fmamk_f32 v116, v116, 0x3a000000, v153
	v_cmp_gt_f32_e32 vcc, s14, v116
	v_mul_f32_e32 v117, 0x4b800000, v116
	s_nop 0
	v_cndmask_b32_e32 v116, v116, v117, vcc
	v_rsq_f32_e32 v116, v116
	s_nop 0
	v_mul_f32_e32 v117, 0x45800000, v116
	v_cndmask_b32_e32 v116, v116, v117, vcc
	v_pk_mul_f32 v[118:119], v[118:119], v[116:117] op_sel_hi:[1,0]
	s_nop 0
	v_mul_f32_e32 v104, 0xbfb8aa3b, v119
	v_exp_f32_e32 v104, v104
	s_nop 0
	v_add_f32_e32 v104, 1.0, v104
	v_rcp_f32_e32 v104, v104
	s_nop 0
	v_mul_f32_e32 v104, v119, v104
	v_mul_f32_e32 v117, v118, v104
	v_pk_mul_f32 v[104:105], v[108:109], v[116:117] op_sel_hi:[1,0]
	s_nop 0
	v_mul_f32_e32 v108, 0xbfb8aa3b, v105
	v_exp_f32_e32 v108, v108
	s_nop 0
	v_add_f32_e32 v108, 1.0, v108
	v_rcp_f32_e32 v108, v108
	s_nop 0
	v_mul_f32_e32 v105, v105, v108
	v_mul_f32_e32 v108, v104, v105
	v_mov_b32_e32 v104, v106
	v_mov_b32_e32 v105, v110
	v_pk_mul_f32 v[104:105], v[104:105], v[116:117] op_sel_hi:[1,0]
	v_mov_b32_e32 v110, v107
	v_mul_f32_e32 v106, 0xbfb8aa3b, v105
	v_exp_f32_e32 v106, v106
	s_nop 0
	v_add_f32_e32 v106, 1.0, v106
	v_rcp_f32_e32 v106, v106
	s_nop 0
	v_mul_f32_e32 v105, v105, v106
	v_mul_f32_e32 v106, v104, v105
	v_pk_mul_f32 v[104:105], v[110:111], v[116:117] op_sel_hi:[1,0]
	s_nop 0
	v_mul_f32_e32 v107, 0xbfb8aa3b, v105
	v_exp_f32_e32 v107, v107
	s_nop 0
	v_add_f32_e32 v107, 1.0, v107
	v_rcp_f32_e32 v107, v107
	s_nop 0
	v_mul_f32_e32 v105, v105, v107
	v_mul_f32_e32 v107, v104, v105
	v_mov_b32_e32 v104, v96
	v_mov_b32_e32 v105, v100
	v_pk_mul_f32 v[104:105], v[104:105], v[116:117] op_sel_hi:[1,0]
	v_mov_b32_e32 v100, v97
	v_mul_f32_e32 v96, 0xbfb8aa3b, v105
	v_exp_f32_e32 v96, v96
	s_nop 0
	v_add_f32_e32 v96, 1.0, v96
	v_rcp_f32_e32 v96, v96
	s_nop 0
	v_mul_f32_e32 v96, v105, v96
	v_mul_f32_e32 v104, v104, v96
	v_pk_mul_f32 v[96:97], v[100:101], v[116:117] op_sel_hi:[1,0]
	s_nop 0
	v_mul_f32_e32 v100, 0xbfb8aa3b, v97
	v_exp_f32_e32 v100, v100
	s_nop 0
	v_add_f32_e32 v100, 1.0, v100
	v_rcp_f32_e32 v100, v100
	s_nop 0
	v_mul_f32_e32 v97, v97, v100
	v_mul_f32_e32 v100, v96, v97
	v_mov_b32_e32 v96, v98
	v_mov_b32_e32 v97, v102
	v_pk_mul_f32 v[96:97], v[96:97], v[116:117] op_sel_hi:[1,0]
	v_mov_b32_e32 v102, v99
	v_mul_f32_e32 v98, 0xbfb8aa3b, v97
	v_exp_f32_e32 v98, v98
	s_nop 0
	v_add_f32_e32 v98, 1.0, v98
	v_rcp_f32_e32 v98, v98
	s_nop 0
	v_mul_f32_e32 v97, v97, v98
	v_mul_f32_e32 v101, v96, v97
	v_pk_mul_f32 v[96:97], v[102:103], v[116:117] op_sel_hi:[1,0]
	s_nop 0
	v_mul_f32_e32 v98, 0xbfb8aa3b, v97
	v_exp_f32_e32 v98, v98
	s_nop 0
	v_add_f32_e32 v98, 1.0, v98
	v_rcp_f32_e32 v98, v98
	s_nop 0
	v_mul_f32_e32 v97, v97, v98
	v_mul_f32_e32 v99, v96, v97
	v_cvt_pk_bf16_f32 v96, v117, v108
	v_cvt_pk_bf16_f32 v97, v106, v107
	v_cvt_pk_bf16_f32 v98, v104, v100
	v_cvt_pk_bf16_f32 v99, v101, v99
	v_mad_i64_i32 v[100:101], s[18:19], v120, s15, v[112:113]
	v_lshl_add_u64 v[100:101], v[100:101], 0, v[114:115]
	global_store_dwordx4 v[100:101], v[96:99], off
	v_or_b32_e32 v100, 32, v159
	s_nop 0
	v_add_u32_e32 v96, s44, v100
	v_ashrrev_i32_e32 v97, 31, v96
	v_lshl_add_u64 v[96:97], v[96:97], 2, s[6:7]
	global_load_dword v96, v[96:97], off
	v_mov_b32_e32 v98, v88
	v_mov_b32_e32 v99, v92
	v_mov_b32_e32 v92, v89
	s_waitcnt vmcnt(0)
	v_fmamk_f32 v96, v96, 0x3a000000, v153
	v_cmp_gt_f32_e32 vcc, s14, v96
	v_mul_f32_e32 v97, 0x4b800000, v96
	s_nop 0
	v_cndmask_b32_e32 v96, v96, v97, vcc
	v_rsq_f32_e32 v96, v96
	s_nop 0
	v_mul_f32_e32 v97, 0x45800000, v96
	v_cndmask_b32_e32 v96, v96, v97, vcc
	v_pk_mul_f32 v[98:99], v[98:99], v[96:97] op_sel_hi:[1,0]
	s_nop 0
	v_mul_f32_e32 v88, 0xbfb8aa3b, v99
	v_exp_f32_e32 v88, v88
	s_nop 0
	v_add_f32_e32 v88, 1.0, v88
	v_rcp_f32_e32 v88, v88
	s_nop 0
	v_mul_f32_e32 v88, v99, v88
	v_mul_f32_e32 v97, v98, v88
	v_pk_mul_f32 v[88:89], v[92:93], v[96:97] op_sel_hi:[1,0]
	s_nop 0
	v_mul_f32_e32 v92, 0xbfb8aa3b, v89
	v_exp_f32_e32 v92, v92
	s_nop 0
	v_add_f32_e32 v92, 1.0, v92
	v_rcp_f32_e32 v92, v92
	s_nop 0
	v_mul_f32_e32 v89, v89, v92
	v_mul_f32_e32 v92, v88, v89
	v_mov_b32_e32 v88, v90
	v_mov_b32_e32 v89, v94
	v_pk_mul_f32 v[88:89], v[88:89], v[96:97] op_sel_hi:[1,0]
	v_mov_b32_e32 v94, v91
	v_mul_f32_e32 v90, 0xbfb8aa3b, v89
	v_exp_f32_e32 v90, v90
	s_nop 0
	v_add_f32_e32 v90, 1.0, v90
	v_rcp_f32_e32 v90, v90
	s_nop 0
	v_mul_f32_e32 v89, v89, v90
	v_mul_f32_e32 v90, v88, v89
	v_pk_mul_f32 v[88:89], v[94:95], v[96:97] op_sel_hi:[1,0]
	s_nop 0
	v_mul_f32_e32 v91, 0xbfb8aa3b, v89
	v_exp_f32_e32 v91, v91
	s_nop 0
	v_add_f32_e32 v91, 1.0, v91
	v_rcp_f32_e32 v91, v91
	s_nop 0
	v_mul_f32_e32 v89, v89, v91
	v_mul_f32_e32 v91, v88, v89
	v_mov_b32_e32 v88, v80
	v_mov_b32_e32 v89, v84
	v_pk_mul_f32 v[88:89], v[88:89], v[96:97] op_sel_hi:[1,0]
	v_mov_b32_e32 v84, v81
	v_mul_f32_e32 v80, 0xbfb8aa3b, v89
	v_exp_f32_e32 v80, v80
	s_nop 0
	v_add_f32_e32 v80, 1.0, v80
	v_rcp_f32_e32 v80, v80
	s_nop 0
	v_mul_f32_e32 v80, v89, v80
	v_mul_f32_e32 v88, v88, v80
	v_pk_mul_f32 v[80:81], v[84:85], v[96:97] op_sel_hi:[1,0]
	s_nop 0
	v_mul_f32_e32 v84, 0xbfb8aa3b, v81
	v_exp_f32_e32 v84, v84
	s_nop 0
	v_add_f32_e32 v84, 1.0, v84
	v_rcp_f32_e32 v84, v84
	s_nop 0
	v_mul_f32_e32 v81, v81, v84
	v_mul_f32_e32 v84, v80, v81
	v_mov_b32_e32 v80, v82
	v_mov_b32_e32 v81, v86
	v_pk_mul_f32 v[80:81], v[80:81], v[96:97] op_sel_hi:[1,0]
	v_mov_b32_e32 v86, v83
	v_mul_f32_e32 v82, 0xbfb8aa3b, v81
	v_exp_f32_e32 v82, v82
	s_nop 0
	v_add_f32_e32 v82, 1.0, v82
	v_rcp_f32_e32 v82, v82
	s_nop 0
	v_mul_f32_e32 v81, v81, v82
	v_mul_f32_e32 v85, v80, v81
	v_pk_mul_f32 v[80:81], v[86:87], v[96:97] op_sel_hi:[1,0]
	s_nop 0
	v_mul_f32_e32 v82, 0xbfb8aa3b, v81
	v_exp_f32_e32 v82, v82
	s_nop 0
	v_add_f32_e32 v82, 1.0, v82
	v_rcp_f32_e32 v82, v82
	s_nop 0
	v_mul_f32_e32 v81, v81, v82
	v_mul_f32_e32 v83, v80, v81
	v_cvt_pk_bf16_f32 v80, v97, v92
	v_cvt_pk_bf16_f32 v81, v90, v91
	v_cvt_pk_bf16_f32 v82, v88, v84
	v_cvt_pk_bf16_f32 v83, v85, v83
	v_mad_i64_i32 v[84:85], s[18:19], v100, s15, v[112:113]
	v_lshl_add_u64 v[84:85], v[84:85], 0, v[114:115]
	global_store_dwordx4 v[84:85], v[80:83], off
	v_or_b32_e32 v84, 48, v159
	s_nop 0
	v_add_u32_e32 v80, s44, v84
	v_ashrrev_i32_e32 v81, 31, v80
	v_lshl_add_u64 v[80:81], v[80:81], 2, s[6:7]
	global_load_dword v80, v[80:81], off
	v_mov_b32_e32 v82, v72
	v_mov_b32_e32 v83, v76
	v_mov_b32_e32 v76, v73
	s_waitcnt vmcnt(0)
	v_fmamk_f32 v80, v80, 0x3a000000, v153
	v_cmp_gt_f32_e32 vcc, s14, v80
	v_mul_f32_e32 v81, 0x4b800000, v80
	s_nop 0
	v_cndmask_b32_e32 v80, v80, v81, vcc
	v_rsq_f32_e32 v80, v80
	s_nop 0
	v_mul_f32_e32 v81, 0x45800000, v80
	v_cndmask_b32_e32 v80, v80, v81, vcc
	v_pk_mul_f32 v[82:83], v[82:83], v[80:81] op_sel_hi:[1,0]
	s_nop 0
	v_mul_f32_e32 v72, 0xbfb8aa3b, v83
	v_exp_f32_e32 v72, v72
	s_nop 0
	v_add_f32_e32 v72, 1.0, v72
	v_rcp_f32_e32 v72, v72
	s_nop 0
	v_mul_f32_e32 v72, v83, v72
	v_mul_f32_e32 v81, v82, v72
	v_pk_mul_f32 v[72:73], v[76:77], v[80:81] op_sel_hi:[1,0]
	s_nop 0
	v_mul_f32_e32 v76, 0xbfb8aa3b, v73
	v_exp_f32_e32 v76, v76
	s_nop 0
	v_add_f32_e32 v76, 1.0, v76
	v_rcp_f32_e32 v76, v76
	s_nop 0
	v_mul_f32_e32 v73, v73, v76
	v_mul_f32_e32 v76, v72, v73
	v_mov_b32_e32 v72, v74
	v_mov_b32_e32 v73, v78
	v_pk_mul_f32 v[72:73], v[72:73], v[80:81] op_sel_hi:[1,0]
	v_mov_b32_e32 v78, v75
	v_mul_f32_e32 v74, 0xbfb8aa3b, v73
	v_exp_f32_e32 v74, v74
	s_nop 0
	v_add_f32_e32 v74, 1.0, v74
	v_rcp_f32_e32 v74, v74
	s_nop 0
	v_mul_f32_e32 v73, v73, v74
	v_mul_f32_e32 v74, v72, v73
	v_pk_mul_f32 v[72:73], v[78:79], v[80:81] op_sel_hi:[1,0]
	s_nop 0
	v_mul_f32_e32 v75, 0xbfb8aa3b, v73
	v_exp_f32_e32 v75, v75
	s_nop 0
	v_add_f32_e32 v75, 1.0, v75
	v_rcp_f32_e32 v75, v75
	s_nop 0
	v_mul_f32_e32 v73, v73, v75
	v_mul_f32_e32 v75, v72, v73
	v_mov_b32_e32 v72, v64
	v_mov_b32_e32 v73, v68
	v_pk_mul_f32 v[72:73], v[72:73], v[80:81] op_sel_hi:[1,0]
	v_mov_b32_e32 v68, v65
	v_mul_f32_e32 v64, 0xbfb8aa3b, v73
	v_exp_f32_e32 v64, v64
	s_nop 0
	v_add_f32_e32 v64, 1.0, v64
	v_rcp_f32_e32 v64, v64
	s_nop 0
	v_mul_f32_e32 v64, v73, v64
	v_mul_f32_e32 v72, v72, v64
	v_pk_mul_f32 v[64:65], v[68:69], v[80:81] op_sel_hi:[1,0]
	s_nop 0
	v_mul_f32_e32 v68, 0xbfb8aa3b, v65
	v_exp_f32_e32 v68, v68
	s_nop 0
	v_add_f32_e32 v68, 1.0, v68
	v_rcp_f32_e32 v68, v68
	s_nop 0
	v_mul_f32_e32 v65, v65, v68
	v_mul_f32_e32 v68, v64, v65
	v_mov_b32_e32 v64, v66
	v_mov_b32_e32 v65, v70
	v_pk_mul_f32 v[64:65], v[64:65], v[80:81] op_sel_hi:[1,0]
	v_mov_b32_e32 v70, v67
	v_mul_f32_e32 v66, 0xbfb8aa3b, v65
	v_exp_f32_e32 v66, v66
	s_nop 0
	v_add_f32_e32 v66, 1.0, v66
	v_rcp_f32_e32 v66, v66
	s_nop 0
	v_mul_f32_e32 v65, v65, v66
	v_mul_f32_e32 v69, v64, v65
	v_pk_mul_f32 v[64:65], v[70:71], v[80:81] op_sel_hi:[1,0]
	s_nop 0
	v_mul_f32_e32 v66, 0xbfb8aa3b, v65
	v_exp_f32_e32 v66, v66
	s_nop 0
	v_add_f32_e32 v66, 1.0, v66
	v_rcp_f32_e32 v66, v66
	s_nop 0
	v_mul_f32_e32 v65, v65, v66
	v_mul_f32_e32 v67, v64, v65
	v_cvt_pk_bf16_f32 v64, v81, v76
	v_cvt_pk_bf16_f32 v65, v74, v75
	v_cvt_pk_bf16_f32 v66, v72, v68
	v_cvt_pk_bf16_f32 v67, v69, v67
	v_mad_i64_i32 v[68:69], s[18:19], v84, s15, v[112:113]
	v_lshl_add_u64 v[68:69], v[68:69], 0, v[114:115]
	global_store_dwordx4 v[68:69], v[64:67], off
	v_add_u32_e32 v68, 0x80, v159
	s_nop 0
	v_add_u32_e32 v64, s44, v68
	v_ashrrev_i32_e32 v65, 31, v64
	v_lshl_add_u64 v[64:65], v[64:65], 2, s[6:7]
	global_load_dword v64, v[64:65], off
	v_mov_b32_e32 v66, v56
	v_mov_b32_e32 v67, v60
	v_mov_b32_e32 v60, v57
	s_waitcnt vmcnt(0)
	v_fmamk_f32 v64, v64, 0x3a000000, v153
	v_cmp_gt_f32_e32 vcc, s14, v64
	v_mul_f32_e32 v65, 0x4b800000, v64
	s_nop 0
	v_cndmask_b32_e32 v64, v64, v65, vcc
	v_rsq_f32_e32 v64, v64
	s_nop 0
	v_mul_f32_e32 v65, 0x45800000, v64
	v_cndmask_b32_e32 v64, v64, v65, vcc
	v_pk_mul_f32 v[66:67], v[66:67], v[64:65] op_sel_hi:[1,0]
	s_nop 0
	v_mul_f32_e32 v56, 0xbfb8aa3b, v67
	v_exp_f32_e32 v56, v56
	s_nop 0
	v_add_f32_e32 v56, 1.0, v56
	v_rcp_f32_e32 v56, v56
	s_nop 0
	v_mul_f32_e32 v56, v67, v56
	v_mul_f32_e32 v65, v66, v56
	v_pk_mul_f32 v[56:57], v[60:61], v[64:65] op_sel_hi:[1,0]
	s_nop 0
	v_mul_f32_e32 v60, 0xbfb8aa3b, v57
	v_exp_f32_e32 v60, v60
	s_nop 0
	v_add_f32_e32 v60, 1.0, v60
	v_rcp_f32_e32 v60, v60
	s_nop 0
	v_mul_f32_e32 v57, v57, v60
	v_mul_f32_e32 v60, v56, v57
	v_mov_b32_e32 v56, v58
	v_mov_b32_e32 v57, v62
	v_pk_mul_f32 v[56:57], v[56:57], v[64:65] op_sel_hi:[1,0]
	v_mov_b32_e32 v62, v59
	v_mul_f32_e32 v58, 0xbfb8aa3b, v57
	v_exp_f32_e32 v58, v58
	s_nop 0
	v_add_f32_e32 v58, 1.0, v58
	v_rcp_f32_e32 v58, v58
	s_nop 0
	v_mul_f32_e32 v57, v57, v58
	v_mul_f32_e32 v58, v56, v57
	v_pk_mul_f32 v[56:57], v[62:63], v[64:65] op_sel_hi:[1,0]
	s_nop 0
	v_mul_f32_e32 v59, 0xbfb8aa3b, v57
	v_exp_f32_e32 v59, v59
	s_nop 0
	v_add_f32_e32 v59, 1.0, v59
	v_rcp_f32_e32 v59, v59
	s_nop 0
	v_mul_f32_e32 v57, v57, v59
	v_mul_f32_e32 v59, v56, v57
	v_mov_b32_e32 v56, v48
	v_mov_b32_e32 v57, v52
	v_pk_mul_f32 v[56:57], v[56:57], v[64:65] op_sel_hi:[1,0]
	v_mov_b32_e32 v52, v49
	v_mul_f32_e32 v48, 0xbfb8aa3b, v57
	v_exp_f32_e32 v48, v48
	s_nop 0
	v_add_f32_e32 v48, 1.0, v48
	v_rcp_f32_e32 v48, v48
	s_nop 0
	v_mul_f32_e32 v48, v57, v48
	v_mul_f32_e32 v56, v56, v48
	v_pk_mul_f32 v[48:49], v[52:53], v[64:65] op_sel_hi:[1,0]
	s_nop 0
	v_mul_f32_e32 v52, 0xbfb8aa3b, v49
	v_exp_f32_e32 v52, v52
	s_nop 0
	v_add_f32_e32 v52, 1.0, v52
	v_rcp_f32_e32 v52, v52
	s_nop 0
	v_mul_f32_e32 v49, v49, v52
	v_mul_f32_e32 v52, v48, v49
	v_mov_b32_e32 v48, v50
	v_mov_b32_e32 v49, v54
	v_pk_mul_f32 v[48:49], v[48:49], v[64:65] op_sel_hi:[1,0]
	v_mov_b32_e32 v54, v51
	v_mul_f32_e32 v50, 0xbfb8aa3b, v49
	v_exp_f32_e32 v50, v50
	s_nop 0
	v_add_f32_e32 v50, 1.0, v50
	v_rcp_f32_e32 v50, v50
	s_nop 0
	v_mul_f32_e32 v49, v49, v50
	v_mul_f32_e32 v53, v48, v49
	v_pk_mul_f32 v[48:49], v[54:55], v[64:65] op_sel_hi:[1,0]
	s_nop 0
	v_mul_f32_e32 v50, 0xbfb8aa3b, v49
	v_exp_f32_e32 v50, v50
	s_nop 0
	v_add_f32_e32 v50, 1.0, v50
	v_rcp_f32_e32 v50, v50
	s_nop 0
	v_mul_f32_e32 v49, v49, v50
	v_mul_f32_e32 v51, v48, v49
	v_cvt_pk_bf16_f32 v48, v65, v60
	v_cvt_pk_bf16_f32 v49, v58, v59
	v_cvt_pk_bf16_f32 v50, v56, v52
	v_cvt_pk_bf16_f32 v51, v53, v51
	v_mad_i64_i32 v[52:53], s[18:19], v68, s15, v[112:113]
	v_lshl_add_u64 v[52:53], v[52:53], 0, v[114:115]
	global_store_dwordx4 v[52:53], v[48:51], off
	v_add_u32_e32 v52, 0x90, v159
	s_nop 0
	v_add_u32_e32 v48, s44, v52
	v_ashrrev_i32_e32 v49, 31, v48
	v_lshl_add_u64 v[48:49], v[48:49], 2, s[6:7]
	global_load_dword v48, v[48:49], off
	v_mov_b32_e32 v50, v40
	v_mov_b32_e32 v51, v44
	v_mov_b32_e32 v44, v41
	s_waitcnt vmcnt(0)
	v_fmamk_f32 v48, v48, 0x3a000000, v153
	v_cmp_gt_f32_e32 vcc, s14, v48
	v_mul_f32_e32 v49, 0x4b800000, v48
	s_nop 0
	v_cndmask_b32_e32 v48, v48, v49, vcc
	v_rsq_f32_e32 v48, v48
	s_nop 0
	v_mul_f32_e32 v49, 0x45800000, v48
	v_cndmask_b32_e32 v48, v48, v49, vcc
	v_pk_mul_f32 v[50:51], v[50:51], v[48:49] op_sel_hi:[1,0]
	s_nop 0
	v_mul_f32_e32 v40, 0xbfb8aa3b, v51
	v_exp_f32_e32 v40, v40
	s_nop 0
	v_add_f32_e32 v40, 1.0, v40
	v_rcp_f32_e32 v40, v40
	s_nop 0
	v_mul_f32_e32 v40, v51, v40
	v_mul_f32_e32 v49, v50, v40
	v_pk_mul_f32 v[40:41], v[44:45], v[48:49] op_sel_hi:[1,0]
	s_nop 0
	v_mul_f32_e32 v44, 0xbfb8aa3b, v41
	v_exp_f32_e32 v44, v44
	s_nop 0
	v_add_f32_e32 v44, 1.0, v44
	v_rcp_f32_e32 v44, v44
	s_nop 0
	v_mul_f32_e32 v41, v41, v44
	v_mul_f32_e32 v44, v40, v41
	v_mov_b32_e32 v40, v42
	v_mov_b32_e32 v41, v46
	v_pk_mul_f32 v[40:41], v[40:41], v[48:49] op_sel_hi:[1,0]
	v_mov_b32_e32 v46, v43
	v_mul_f32_e32 v42, 0xbfb8aa3b, v41
	v_exp_f32_e32 v42, v42
	s_nop 0
	v_add_f32_e32 v42, 1.0, v42
	v_rcp_f32_e32 v42, v42
	s_nop 0
	v_mul_f32_e32 v41, v41, v42
	v_mul_f32_e32 v42, v40, v41
	v_pk_mul_f32 v[40:41], v[46:47], v[48:49] op_sel_hi:[1,0]
	s_nop 0
	v_mul_f32_e32 v43, 0xbfb8aa3b, v41
	v_exp_f32_e32 v43, v43
	s_nop 0
	v_add_f32_e32 v43, 1.0, v43
	v_rcp_f32_e32 v43, v43
	s_nop 0
	v_mul_f32_e32 v41, v41, v43
	v_mul_f32_e32 v43, v40, v41
	v_mov_b32_e32 v40, v32
	v_mov_b32_e32 v41, v36
	v_pk_mul_f32 v[40:41], v[40:41], v[48:49] op_sel_hi:[1,0]
	v_mov_b32_e32 v36, v33
	v_mul_f32_e32 v32, 0xbfb8aa3b, v41
	v_exp_f32_e32 v32, v32
	s_nop 0
	v_add_f32_e32 v32, 1.0, v32
	v_rcp_f32_e32 v32, v32
	s_nop 0
	v_mul_f32_e32 v32, v41, v32
	v_mul_f32_e32 v40, v40, v32
	v_pk_mul_f32 v[32:33], v[36:37], v[48:49] op_sel_hi:[1,0]
	s_nop 0
	v_mul_f32_e32 v36, 0xbfb8aa3b, v33
	v_exp_f32_e32 v36, v36
	s_nop 0
	v_add_f32_e32 v36, 1.0, v36
	v_rcp_f32_e32 v36, v36
	s_nop 0
	v_mul_f32_e32 v33, v33, v36
	v_mul_f32_e32 v36, v32, v33
	v_mov_b32_e32 v32, v34
	v_mov_b32_e32 v33, v38
	v_pk_mul_f32 v[32:33], v[32:33], v[48:49] op_sel_hi:[1,0]
	v_mov_b32_e32 v38, v35
	v_mul_f32_e32 v34, 0xbfb8aa3b, v33
	v_exp_f32_e32 v34, v34
	s_nop 0
	v_add_f32_e32 v34, 1.0, v34
	v_rcp_f32_e32 v34, v34
	s_nop 0
	v_mul_f32_e32 v33, v33, v34
	v_mul_f32_e32 v37, v32, v33
	v_pk_mul_f32 v[32:33], v[38:39], v[48:49] op_sel_hi:[1,0]
	s_nop 0
	v_mul_f32_e32 v34, 0xbfb8aa3b, v33
	v_exp_f32_e32 v34, v34
	s_nop 0
	v_add_f32_e32 v34, 1.0, v34
	v_rcp_f32_e32 v34, v34
	s_nop 0
	v_mul_f32_e32 v33, v33, v34
	v_mul_f32_e32 v35, v32, v33
	v_cvt_pk_bf16_f32 v32, v49, v44
	v_cvt_pk_bf16_f32 v33, v42, v43
	v_cvt_pk_bf16_f32 v34, v40, v36
	v_cvt_pk_bf16_f32 v35, v37, v35
	v_mad_i64_i32 v[36:37], s[18:19], v52, s15, v[112:113]
	v_lshl_add_u64 v[36:37], v[36:37], 0, v[114:115]
	global_store_dwordx4 v[36:37], v[32:35], off
	v_add_u32_e32 v36, 0xa0, v159
	s_nop 0
	v_add_u32_e32 v32, s44, v36
	v_ashrrev_i32_e32 v33, 31, v32
	v_lshl_add_u64 v[32:33], v[32:33], 2, s[6:7]
	global_load_dword v32, v[32:33], off
	v_mov_b32_e32 v34, v24
	v_mov_b32_e32 v35, v28
	v_mov_b32_e32 v28, v25
	s_waitcnt vmcnt(0)
	v_fmamk_f32 v32, v32, 0x3a000000, v153
	v_cmp_gt_f32_e32 vcc, s14, v32
	v_mul_f32_e32 v33, 0x4b800000, v32
	s_nop 0
	v_cndmask_b32_e32 v32, v32, v33, vcc
	v_rsq_f32_e32 v32, v32
	s_nop 0
	v_mul_f32_e32 v33, 0x45800000, v32
	v_cndmask_b32_e32 v32, v32, v33, vcc
	v_pk_mul_f32 v[34:35], v[34:35], v[32:33] op_sel_hi:[1,0]
	s_nop 0
	v_mul_f32_e32 v24, 0xbfb8aa3b, v35
	v_exp_f32_e32 v24, v24
	s_nop 0
	v_add_f32_e32 v24, 1.0, v24
	v_rcp_f32_e32 v24, v24
	s_nop 0
	v_mul_f32_e32 v24, v35, v24
	v_mul_f32_e32 v33, v34, v24
	v_pk_mul_f32 v[24:25], v[28:29], v[32:33] op_sel_hi:[1,0]
	s_nop 0
	v_mul_f32_e32 v28, 0xbfb8aa3b, v25
	v_exp_f32_e32 v28, v28
	s_nop 0
	v_add_f32_e32 v28, 1.0, v28
	v_rcp_f32_e32 v28, v28
	s_nop 0
	v_mul_f32_e32 v25, v25, v28
	v_mul_f32_e32 v28, v24, v25
	v_mov_b32_e32 v24, v26
	v_mov_b32_e32 v25, v30
	v_pk_mul_f32 v[24:25], v[24:25], v[32:33] op_sel_hi:[1,0]
	v_mov_b32_e32 v30, v27
	v_mul_f32_e32 v26, 0xbfb8aa3b, v25
	v_exp_f32_e32 v26, v26
	s_nop 0
	v_add_f32_e32 v26, 1.0, v26
	v_rcp_f32_e32 v26, v26
	s_nop 0
	v_mul_f32_e32 v25, v25, v26
	v_mul_f32_e32 v26, v24, v25
	v_pk_mul_f32 v[24:25], v[30:31], v[32:33] op_sel_hi:[1,0]
	s_nop 0
	v_mul_f32_e32 v27, 0xbfb8aa3b, v25
	v_exp_f32_e32 v27, v27
	s_nop 0
	v_add_f32_e32 v27, 1.0, v27
	v_rcp_f32_e32 v27, v27
	s_nop 0
	v_mul_f32_e32 v25, v25, v27
	v_mul_f32_e32 v27, v24, v25
	v_mov_b32_e32 v24, v16
	v_mov_b32_e32 v25, v20
	v_pk_mul_f32 v[24:25], v[24:25], v[32:33] op_sel_hi:[1,0]
	v_mov_b32_e32 v20, v17
	v_mul_f32_e32 v16, 0xbfb8aa3b, v25
	v_exp_f32_e32 v16, v16
	s_nop 0
	v_add_f32_e32 v16, 1.0, v16
	v_rcp_f32_e32 v16, v16
	s_nop 0
	v_mul_f32_e32 v16, v25, v16
	v_mul_f32_e32 v24, v24, v16
	v_pk_mul_f32 v[16:17], v[20:21], v[32:33] op_sel_hi:[1,0]
	s_nop 0
	v_mul_f32_e32 v20, 0xbfb8aa3b, v17
	v_exp_f32_e32 v20, v20
	s_nop 0
	v_add_f32_e32 v20, 1.0, v20
	v_rcp_f32_e32 v20, v20
	s_nop 0
	v_mul_f32_e32 v17, v17, v20
	v_mul_f32_e32 v20, v16, v17
	v_mov_b32_e32 v16, v18
	v_mov_b32_e32 v17, v22
	v_pk_mul_f32 v[16:17], v[16:17], v[32:33] op_sel_hi:[1,0]
	v_mov_b32_e32 v22, v19
	v_mul_f32_e32 v18, 0xbfb8aa3b, v17
	v_exp_f32_e32 v18, v18
	s_nop 0
	v_add_f32_e32 v18, 1.0, v18
	v_rcp_f32_e32 v18, v18
	s_nop 0
	v_mul_f32_e32 v17, v17, v18
	v_mul_f32_e32 v21, v16, v17
	v_pk_mul_f32 v[16:17], v[22:23], v[32:33] op_sel_hi:[1,0]
	s_nop 0
	v_mul_f32_e32 v18, 0xbfb8aa3b, v17
	v_exp_f32_e32 v18, v18
	s_nop 0
	v_add_f32_e32 v18, 1.0, v18
	v_rcp_f32_e32 v18, v18
	s_nop 0
	v_mul_f32_e32 v17, v17, v18
	v_mul_f32_e32 v19, v16, v17
	v_cvt_pk_bf16_f32 v16, v33, v28
	v_cvt_pk_bf16_f32 v17, v26, v27
	v_cvt_pk_bf16_f32 v18, v24, v20
	v_cvt_pk_bf16_f32 v19, v21, v19
	v_mad_i64_i32 v[20:21], s[18:19], v36, s15, v[112:113]
	v_lshl_add_u64 v[20:21], v[20:21], 0, v[114:115]
	global_store_dwordx4 v[20:21], v[16:19], off
	v_add_u32_e32 v20, 0xb0, v159
	s_nop 0
	v_add_u32_e32 v16, s44, v20
	v_ashrrev_i32_e32 v17, 31, v16
	v_lshl_add_u64 v[16:17], v[16:17], 2, s[6:7]
	global_load_dword v16, v[16:17], off
	v_mov_b32_e32 v18, v8
	v_mov_b32_e32 v19, v12
	v_mov_b32_e32 v12, v9
	s_waitcnt vmcnt(0)
	v_fmamk_f32 v16, v16, 0x3a000000, v153
	v_cmp_gt_f32_e32 vcc, s14, v16
	v_mul_f32_e32 v17, 0x4b800000, v16
	s_nop 0
	v_cndmask_b32_e32 v16, v16, v17, vcc
	v_rsq_f32_e32 v16, v16
	s_nop 0
	v_mul_f32_e32 v17, 0x45800000, v16
	v_cndmask_b32_e32 v16, v16, v17, vcc
	v_pk_mul_f32 v[18:19], v[18:19], v[16:17] op_sel_hi:[1,0]
	s_andn2_b64 vcc, exec, s[38:39]
	v_mul_f32_e32 v8, 0xbfb8aa3b, v19
	v_exp_f32_e32 v8, v8
	s_nop 0
	v_add_f32_e32 v8, 1.0, v8
	v_rcp_f32_e32 v8, v8
	s_nop 0
	v_mul_f32_e32 v8, v19, v8
	v_mul_f32_e32 v17, v18, v8
	v_pk_mul_f32 v[8:9], v[12:13], v[16:17] op_sel_hi:[1,0]
	s_nop 0
	v_mul_f32_e32 v12, 0xbfb8aa3b, v9
	v_exp_f32_e32 v12, v12
	s_nop 0
	v_add_f32_e32 v12, 1.0, v12
	v_rcp_f32_e32 v12, v12
	s_nop 0
	v_mul_f32_e32 v9, v9, v12
	v_mul_f32_e32 v12, v8, v9
	v_mov_b32_e32 v8, v10
	v_mov_b32_e32 v9, v14
	v_pk_mul_f32 v[8:9], v[8:9], v[16:17] op_sel_hi:[1,0]
	v_mov_b32_e32 v14, v11
	v_mul_f32_e32 v10, 0xbfb8aa3b, v9
	v_exp_f32_e32 v10, v10
	s_nop 0
	v_add_f32_e32 v10, 1.0, v10
	v_rcp_f32_e32 v10, v10
	s_nop 0
	v_mul_f32_e32 v9, v9, v10
	v_mul_f32_e32 v10, v8, v9
	v_pk_mul_f32 v[8:9], v[14:15], v[16:17] op_sel_hi:[1,0]
	s_nop 0
	v_mul_f32_e32 v11, 0xbfb8aa3b, v9
	v_exp_f32_e32 v11, v11
	s_nop 0
	v_add_f32_e32 v11, 1.0, v11
	v_rcp_f32_e32 v11, v11
	s_nop 0
	v_mul_f32_e32 v9, v9, v11
	v_mul_f32_e32 v11, v8, v9
	v_mov_b32_e32 v8, v0
	v_mov_b32_e32 v9, v4
	v_pk_mul_f32 v[8:9], v[8:9], v[16:17] op_sel_hi:[1,0]
	v_mov_b32_e32 v4, v1
	v_mul_f32_e32 v0, 0xbfb8aa3b, v9
	v_exp_f32_e32 v0, v0
	s_nop 0
	v_add_f32_e32 v0, 1.0, v0
	v_rcp_f32_e32 v0, v0
	s_nop 0
	v_mul_f32_e32 v0, v9, v0
	v_mul_f32_e32 v8, v8, v0
	v_pk_mul_f32 v[0:1], v[4:5], v[16:17] op_sel_hi:[1,0]
	s_nop 0
	v_mul_f32_e32 v4, 0xbfb8aa3b, v1
	v_exp_f32_e32 v4, v4
	s_nop 0
	v_add_f32_e32 v4, 1.0, v4
	v_rcp_f32_e32 v4, v4
	s_nop 0
	v_mul_f32_e32 v1, v1, v4
	v_mul_f32_e32 v4, v0, v1
	v_mov_b32_e32 v0, v2
	v_mov_b32_e32 v1, v6
	v_pk_mul_f32 v[0:1], v[0:1], v[16:17] op_sel_hi:[1,0]
	v_mov_b32_e32 v6, v3
	v_mul_f32_e32 v2, 0xbfb8aa3b, v1
	v_exp_f32_e32 v2, v2
	s_nop 0
	v_add_f32_e32 v2, 1.0, v2
	v_rcp_f32_e32 v2, v2
	s_nop 0
	v_mul_f32_e32 v1, v1, v2
	v_mul_f32_e32 v5, v0, v1
	v_pk_mul_f32 v[0:1], v[6:7], v[16:17] op_sel_hi:[1,0]
	s_nop 0
	v_mul_f32_e32 v2, 0xbfb8aa3b, v1
	v_exp_f32_e32 v2, v2
	s_nop 0
	v_add_f32_e32 v2, 1.0, v2
	v_rcp_f32_e32 v2, v2
	s_nop 0
	v_mul_f32_e32 v1, v1, v2
	v_mul_f32_e32 v3, v0, v1
	v_cvt_pk_bf16_f32 v0, v17, v12
	v_cvt_pk_bf16_f32 v1, v10, v11
	v_cvt_pk_bf16_f32 v2, v8, v4
	v_cvt_pk_bf16_f32 v3, v5, v3
	v_mad_i64_i32 v[4:5], s[18:19], v20, s15, v[112:113]
	v_lshl_add_u64 v[4:5], v[4:5], 0, v[114:115]
	s_cmp_eq_u32 s59, 1
	s_cbranch_scc0 .Lfn_skip_st
	s_cmp_lt_u32 s99, 16
	s_cbranch_scc0 .Lfn_skip_st
	v_fmamk_f32 v212, v212, 0x3a000000, v153
	v_rsq_f32_e32 v212, v212
	s_nop 0
	v_lshlrev_b32_e32 v220, 16, v164
	v_and_b32_e32 v221, 0xffff0000, v164
	v_lshlrev_b32_e32 v222, 16, v165
	v_and_b32_e32 v223, 0xffff0000, v165
	v_lshlrev_b32_e32 v224, 16, v166
	v_and_b32_e32 v225, 0xffff0000, v166
	v_lshlrev_b32_e32 v226, 16, v167
	v_and_b32_e32 v227, 0xffff0000, v167
	v_pk_mul_f32 v[220:221], v[212:213], v[220:221] op_sel_hi:[0,1]
	v_pk_mul_f32 v[222:223], v[212:213], v[222:223] op_sel_hi:[0,1]
	v_pk_mul_f32 v[224:225], v[212:213], v[224:225] op_sel_hi:[0,1]
	v_pk_mul_f32 v[226:227], v[212:213], v[226:227] op_sel_hi:[0,1]
	v_pk_mul_f32 v[220:221], v[180:181], v[220:221]
	v_pk_mul_f32 v[222:223], v[182:183], v[222:223]
	v_pk_mul_f32 v[224:225], v[184:185], v[224:225]
	v_pk_mul_f32 v[226:227], v[186:187], v[226:227]
	global_store_dwordx4 v[218:219], v[220:223], off offset:-4096
	global_store_dwordx4 v[218:219], v[224:227], off offset:-4080
	s_nop 1
	v_lshlrev_b32_e32 v220, 16, v168
	v_and_b32_e32 v221, 0xffff0000, v168
	v_lshlrev_b32_e32 v222, 16, v169
	v_and_b32_e32 v223, 0xffff0000, v169
	v_lshlrev_b32_e32 v224, 16, v170
	v_and_b32_e32 v225, 0xffff0000, v170
	v_lshlrev_b32_e32 v226, 16, v171
	v_and_b32_e32 v227, 0xffff0000, v171
	v_pk_mul_f32 v[220:221], v[212:213], v[220:221] op_sel_hi:[0,1]
	v_pk_mul_f32 v[222:223], v[212:213], v[222:223] op_sel_hi:[0,1]
	v_pk_mul_f32 v[224:225], v[212:213], v[224:225] op_sel_hi:[0,1]
	v_pk_mul_f32 v[226:227], v[212:213], v[226:227] op_sel_hi:[0,1]
	v_pk_mul_f32 v[220:221], v[188:189], v[220:221]
	v_pk_mul_f32 v[222:223], v[190:191], v[222:223]
	v_pk_mul_f32 v[224:225], v[192:193], v[224:225]
	v_pk_mul_f32 v[226:227], v[194:195], v[226:227]
	global_store_dwordx4 v[218:219], v[220:223], off offset:-2048
	global_store_dwordx4 v[218:219], v[224:227], off offset:-2032
	s_nop 1
	v_lshlrev_b32_e32 v220, 16, v172
	v_and_b32_e32 v221, 0xffff0000, v172
	v_lshlrev_b32_e32 v222, 16, v173
	v_and_b32_e32 v223, 0xffff0000, v173
	v_lshlrev_b32_e32 v224, 16, v174
	v_and_b32_e32 v225, 0xffff0000, v174
	v_lshlrev_b32_e32 v226, 16, v175
	v_and_b32_e32 v227, 0xffff0000, v175
	v_pk_mul_f32 v[220:221], v[212:213], v[220:221] op_sel_hi:[0,1]
	v_pk_mul_f32 v[222:223], v[212:213], v[222:223] op_sel_hi:[0,1]
	v_pk_mul_f32 v[224:225], v[212:213], v[224:225] op_sel_hi:[0,1]
	v_pk_mul_f32 v[226:227], v[212:213], v[226:227] op_sel_hi:[0,1]
	v_pk_mul_f32 v[220:221], v[196:197], v[220:221]
	v_pk_mul_f32 v[222:223], v[198:199], v[222:223]
	v_pk_mul_f32 v[224:225], v[200:201], v[224:225]
	v_pk_mul_f32 v[226:227], v[202:203], v[226:227]
	global_store_dwordx4 v[218:219], v[220:223], off offset:0
	global_store_dwordx4 v[218:219], v[224:227], off offset:16
	s_nop 1
	v_lshlrev_b32_e32 v220, 16, v176
	v_and_b32_e32 v221, 0xffff0000, v176
	v_lshlrev_b32_e32 v222, 16, v177
	v_and_b32_e32 v223, 0xffff0000, v177
	v_lshlrev_b32_e32 v224, 16, v178
	v_and_b32_e32 v225, 0xffff0000, v178
	v_lshlrev_b32_e32 v226, 16, v179
	v_and_b32_e32 v227, 0xffff0000, v179
	v_pk_mul_f32 v[220:221], v[212:213], v[220:221] op_sel_hi:[0,1]
	v_pk_mul_f32 v[222:223], v[212:213], v[222:223] op_sel_hi:[0,1]
	v_pk_mul_f32 v[224:225], v[212:213], v[224:225] op_sel_hi:[0,1]
	v_pk_mul_f32 v[226:227], v[212:213], v[226:227] op_sel_hi:[0,1]
	v_pk_mul_f32 v[220:221], v[204:205], v[220:221]
	v_pk_mul_f32 v[222:223], v[206:207], v[222:223]
	v_pk_mul_f32 v[224:225], v[208:209], v[224:225]
	v_pk_mul_f32 v[226:227], v[210:211], v[226:227]
	global_store_dwordx4 v[218:219], v[220:223], off offset:2048
	global_store_dwordx4 v[218:219], v[224:227], off offset:2064
	s_nop 1
	s_add_u32 s99, s99, 1
.Lfn_skip_st:
	s_mov_b64 s[18:19], -1
	global_store_dwordx4 v[4:5], v[0:3], off
	s_cbranch_vccnz .LBB0_686
	s_andn2_b64 vcc, exec, s[40:41]
	s_cbranch_vccnz .LBB0_685
	s_barrier
	s_branch .LBB0_685

.LBB0_871:
	s_cmp_gt_i32 s94, 10
	s_cselect_b64 s[0:1], -1, 0
	s_xor_b64 s[2:3], s[2:3], -1
	s_or_b64 s[0:1], s[0:1], s[2:3]
	s_and_b64 vcc, exec, s[0:1]
	s_cbranch_vccnz .LBB0_875
	s_load_dword s0, s[42:43], 0x0
	v_and_b32_e32 v1, 63, v150
	v_lshrrev_b32_e32 v2, 6, v150
	v_mov_b32_e32 v14, 0x358637bd
	s_mov_b32 s22, 0x800000
	v_readfirstlane_b32 s1, v151
	v_readfirstlane_b32 s11, v2
	s_waitcnt lgkmcnt(0)
	s_lshl_b32 s2, s1, 3
	s_add_u32 s10, s2, s11
	s_add_u32 s10, s10, 0x8000
	s_lshl_b32 s23, s0, 3
	s_lshl_b32 s12, s23, 12
	s_mov_b32 s13, 0
	s_lshl_b32 s18, s23, 2
	s_mov_b32 s19, 0
	s_lshl_b32 s20, s23, 13
	s_mov_b32 s21, 0
	v_lshlrev_b32_e32 v10, 5, v1
	v_mov_b32_e32 v11, 0
	v_lshl_add_u64 v[10:11], s[88:89], 0, v[10:11]
	s_mov_b64 s[14:15], 0x1000
	v_lshl_add_u64 v[12:13], v[10:11], 0, s[14:15]
	global_load_dwordx4 v[16:19], v[10:11], off
	global_load_dwordx4 v[20:23], v[10:11], off offset:16
	global_load_dwordx4 v[24:27], v[10:11], off offset:2048
	global_load_dwordx4 v[28:31], v[10:11], off offset:2064
	global_load_dwordx4 v[32:35], v[12:13], off
	global_load_dwordx4 v[36:39], v[12:13], off offset:16
	global_load_dwordx4 v[40:43], v[12:13], off offset:2048
	global_load_dwordx4 v[44:47], v[12:13], off offset:2064
	s_lshl_b32 s14, s10, 12
	v_lshlrev_b32_e32 v4, 4, v1
	v_add_u32_e32 v4, s14, v4
	v_mov_b32_e32 v5, 0
	s_add_u32 s16, s92, 0x6400000
	s_addc_u32 s17, s93, 0
	v_lshl_add_u64 v[4:5], s[16:17], 0, v[4:5]
	s_lshl_b32 s14, s10, 2
	v_mov_b32_e32 v6, s14
	v_mov_b32_e32 v7, 0
	s_add_u32 s16, s92, 0x5f80000
	s_addc_u32 s17, s93, 0
	v_lshl_add_u64 v[6:7], s[16:17], 0, v[6:7]
	s_lshl_b32 s14, s10, 13
	s_add_u32 s14, s14, 0x1000
	v_lshlrev_b32_e32 v8, 5, v1
	v_add_u32_e32 v8, s14, v8
	v_mov_b32_e32 v9, 0
	v_lshl_add_u64 v[8:9], s[90:91], 0, v[8:9]
	global_load_dword v144, v[6:7], off
	global_load_dwordx4 v[80:83], v[4:5], off
	global_load_dwordx4 v[84:87], v[4:5], off offset:1024
	global_load_dwordx4 v[88:91], v[4:5], off offset:2048
	global_load_dwordx4 v[92:95], v[4:5], off offset:3072
	v_lshl_add_u64 v[4:5], v[4:5], 0, s[12:13]
	v_lshl_add_u64 v[6:7], v[6:7], 0, s[18:19]
	global_load_dword v145, v[6:7], off
	global_load_dwordx4 v[96:99], v[4:5], off
	global_load_dwordx4 v[100:103], v[4:5], off offset:1024
	global_load_dwordx4 v[104:107], v[4:5], off offset:2048
	global_load_dwordx4 v[108:111], v[4:5], off offset:3072
	v_lshl_add_u64 v[4:5], v[4:5], 0, s[12:13]
	v_lshl_add_u64 v[6:7], v[6:7], 0, s[18:19]
	global_load_dword v146, v[6:7], off
	global_load_dwordx4 v[112:115], v[4:5], off
	global_load_dwordx4 v[116:119], v[4:5], off offset:1024
	global_load_dwordx4 v[120:123], v[4:5], off offset:2048
	global_load_dwordx4 v[124:127], v[4:5], off offset:3072
	v_lshl_add_u64 v[4:5], v[4:5], 0, s[12:13]
	v_lshl_add_u64 v[6:7], v[6:7], 0, s[18:19]
	global_load_dword v147, v[6:7], off
	global_load_dwordx4 v[128:131], v[4:5], off
	global_load_dwordx4 v[132:135], v[4:5], off offset:1024
	global_load_dwordx4 v[136:139], v[4:5], off offset:2048
	global_load_dwordx4 v[140:143], v[4:5], off offset:3072
	v_lshl_add_u64 v[4:5], v[4:5], 0, s[12:13]
	v_lshl_add_u64 v[6:7], v[6:7], 0, s[18:19]
	s_waitcnt vmcnt(0)
